# inproj K-loop rewritten: loads, LDS writes and fragment reads interleaved into MFMA gaps (3 fragment register sets), last iteration via original code
# speedup vs baseline: 1.0089x; 1.0089x over previous
; DI void gemm_ldg(const bf16_t* ga, const bf16_t* gb, int lda, int ldb, int koff, u32x4 (&ra)[4], u32x4 (&rb)[4]) {
; #pragma unroll
;   for (int i = 0; i < 4; ++i) {
;     ra[i] = *(const u32x4*)(ga + (size_t)(32 * i) * lda + koff);
;     rb[i] = *(const u32x4*)(gb + (size_t)(32 * i) * ldb + koff);
;   }
; }
; DI void gemm_sts(bf16_t* dA, bf16_t* dB, int r0, int c0, const u32x4 (&ra)[4], const u32x4 (&rb)[4]) {
; #pragma unroll
;   for (int i = 0; i < 4; ++i) {
;     *(u32x4*)(dA + (r0 + 32 * i) * LDT + c0 * 8) = ra[i];
;     *(u32x4*)(dB + (r0 + 32 * i) * LDT + c0 * 8) = rb[i];
;   }
; }
; DI void gemm_mma(const bf16_t* a_, const bf16_t* b_, f32x16 (&acc)[2][2]) {
;   __builtin_amdgcn_s_setprio(1);
; #pragma unroll
;   for (int kk = 0; kk < 4; ++kk) {
;     bf16x8 a0 = *(const bf16x8*)(a_ + kk * 16);
;     bf16x8 a1 = *(const bf16x8*)(a_ + 32 * LDT + kk * 16);
;     bf16x8 b0 = *(const bf16x8*)(b_ + kk * 16);
;     bf16x8 b1 = *(const bf16x8*)(b_ + 32 * LDT + kk * 16);
;     acc[0][0] = MFMA(a0, b0, acc[0][0]);
;     acc[0][1] = MFMA(a0, b1, acc[0][1]);
;     acc[1][0] = MFMA(a1, b0, acc[1][0]);
;     acc[1][1] = MFMA(a1, b1, acc[1][1]);
;   }
;   __builtin_amdgcn_s_setprio(0);
; }
; DI void gemm_tile(const bf16_t* __restrict__ A, int lda, const bf16_t* __restrict__ B, int ldb, int K,
;                   f32x16 (&acc)[2][2], char* smem) {
;   const int tid = threadIdx.x, lane = tid & 63, w = tid >> 6, wm = w >> 1, wn = w & 1;
;   bf16_t* sA = (bf16_t*)smem;
;   bf16_t* sB = sA + 2 * 128 * LDT;
;   const int r0 = tid >> 3, c0 = tid & 7;
;   const bf16_t* ga = A + (size_t)r0 * lda + c0 * 8;
;   const bf16_t* gb = B + (size_t)r0 * ldb + c0 * 8;
;   const int aoff = (wm * 64 + (lane & 31)) * LDT + (lane >> 5) * 8;
;   const int boff = (wn * 64 + (lane & 31)) * LDT + (lane >> 5) * 8;
;   u32x4 ra0[4], rb0[4], ra1[4], rb1[4];
;   gemm_ldg(ga, gb, lda, ldb, 0, ra0, rb0);
;   gemm_ldg(ga, gb, lda, ldb, 64, ra1, rb1);
;   __syncthreads();
;   gemm_sts(sA, sB, r0, c0, ra0, rb0);
;   __syncthreads();
;   const int nk = K >> 6;
; #pragma unroll 1
;   for (int kt = 0; kt < nk; kt += 2) {
;     if (kt + 2 < nk) gemm_ldg(ga, gb, lda, ldb, (kt + 2) * 64, ra0, rb0);
;     gemm_mma(sA + aoff, sB + boff, acc);
;     gemm_sts(sA + 128 * LDT, sB + 128 * LDT, r0, c0, ra1, rb1);
;     __syncthreads();
;     if (kt + 3 < nk) gemm_ldg(ga, gb, lda, ldb, (kt + 3) * 64, ra1, rb1);
.Lfast1_top:
	ds_read_b128 v[166:169], v156
	ds_read_b128 v[170:173], v157 offset:36864
	ds_read_b128 v[174:177], v157 offset:41472
	ds_read_b128 v[178:181], v156 offset:4608
	ds_read_b128 v[182:185], v156 offset:32
	ds_read_b128 v[186:189], v157 offset:36896
	ds_read_b128 v[190:193], v157 offset:41504
	ds_read_b128 v[194:197], v156 offset:4640
	global_load_dwordx4 v[66:69], v216, s[84:85] offset:256
	global_load_dwordx4 v[70:73], v217, s[84:85] offset:256
	global_load_dwordx4 v[74:77], v217, s[86:87] offset:256
	global_load_dwordx4 v[78:81], v218, s[84:85] offset:256
	s_setprio 1
	s_waitcnt lgkmcnt(6)
	v_mfma_f32_32x32x16_bf16 v[50:65], v[166:169], v[170:173], v[50:65]
	ds_read_b128 v[198:201], v156 offset:64
	global_load_dwordx4 v[82:85], v218, s[86:87] offset:256
	s_waitcnt lgkmcnt(6)
	v_mfma_f32_32x32x16_bf16 v[34:49], v[166:169], v[174:177], v[34:49]
	ds_read_b128 v[202:205], v157 offset:36928
	global_load_dwordx4 v[86:89], v219, s[84:85] offset:256
	s_waitcnt lgkmcnt(6)
	v_mfma_f32_32x32x16_bf16 v[18:33], v[178:181], v[170:173], v[18:33]
	ds_read_b128 v[206:209], v157 offset:41536
	global_load_dwordx4 v[90:93], v216, s[86:87] offset:256
	v_mfma_f32_32x32x16_bf16 v[2:17], v[178:181], v[174:177], v[2:17]
	ds_read_b128 v[210:213], v156 offset:4672
	global_load_dwordx4 v[102:105], v219, s[86:87] offset:256
	s_waitcnt lgkmcnt(6)
	v_mfma_f32_32x32x16_bf16 v[50:65], v[182:185], v[186:189], v[50:65]
	ds_read_b128 v[166:169], v156 offset:96
	s_waitcnt vmcnt(8)
	ds_write_b128 v1, v[94:97] offset:18432
	s_waitcnt lgkmcnt(7)
	v_mfma_f32_32x32x16_bf16 v[34:49], v[182:185], v[190:193], v[34:49]
	ds_read_b128 v[170:173], v157 offset:36960
	ds_write_b128 v1, v[122:125] offset:55296
	s_waitcnt lgkmcnt(8)
	v_mfma_f32_32x32x16_bf16 v[18:33], v[194:197], v[186:189], v[18:33]
	ds_read_b128 v[174:177], v157 offset:41568
	ds_write_b128 v1, v[98:101] offset:23040
	v_mfma_f32_32x32x16_bf16 v[2:17], v[194:197], v[190:193], v[2:17]
	ds_read_b128 v[178:181], v156 offset:4704
	ds_write_b128 v1, v[106:109] offset:59904
	s_waitcnt lgkmcnt(10)
	v_mfma_f32_32x32x16_bf16 v[50:65], v[198:201], v[202:205], v[50:65]
	ds_write_b128 v1, v[110:113] offset:27648
	s_waitcnt lgkmcnt(10)
	v_mfma_f32_32x32x16_bf16 v[34:49], v[198:201], v[206:209], v[34:49]
	ds_write_b128 v1, v[114:117] offset:64512
	s_waitcnt lgkmcnt(10)
	v_mfma_f32_32x32x16_bf16 v[18:33], v[210:213], v[202:205], v[18:33]
	ds_write_b128 v1, v[118:121] offset:32256
	v_mfma_f32_32x32x16_bf16 v[2:17], v[210:213], v[206:209], v[2:17]
	ds_write_b128 v158, v[126:129] offset:13824
	s_waitcnt lgkmcnt(9)
	v_mfma_f32_32x32x16_bf16 v[50:65], v[166:169], v[170:173], v[50:65]
	s_waitcnt lgkmcnt(7)
	v_mfma_f32_32x32x16_bf16 v[34:49], v[166:169], v[174:177], v[34:49]
	s_waitcnt lgkmcnt(5)
	v_mfma_f32_32x32x16_bf16 v[18:33], v[178:181], v[170:173], v[18:33]
	v_mfma_f32_32x32x16_bf16 v[2:17], v[178:181], v[174:177], v[2:17]
	s_setprio 0
	s_waitcnt lgkmcnt(0)
	s_barrier
	ds_read_b128 v[166:169], v156 offset:18432
	ds_read_b128 v[170:173], v157 offset:55296
	ds_read_b128 v[174:177], v157 offset:59904
	ds_read_b128 v[178:181], v156 offset:23040
	ds_read_b128 v[182:185], v156 offset:18464
	ds_read_b128 v[186:189], v157 offset:55328
	ds_read_b128 v[190:193], v157 offset:59936
	ds_read_b128 v[194:197], v156 offset:23072
	global_load_dwordx4 v[94:97], v216, s[84:85] offset:384
	global_load_dwordx4 v[98:101], v217, s[84:85] offset:384
	global_load_dwordx4 v[106:109], v217, s[86:87] offset:384
	global_load_dwordx4 v[110:113], v218, s[84:85] offset:384
	s_setprio 1
	s_waitcnt lgkmcnt(6)
	v_mfma_f32_32x32x16_bf16 v[50:65], v[166:169], v[170:173], v[50:65]
	ds_read_b128 v[198:201], v156 offset:18496
	global_load_dwordx4 v[114:117], v218, s[86:87] offset:384
	s_waitcnt lgkmcnt(6)
	v_mfma_f32_32x32x16_bf16 v[34:49], v[166:169], v[174:177], v[34:49]
	ds_read_b128 v[202:205], v157 offset:55360
	global_load_dwordx4 v[118:121], v219, s[84:85] offset:384
	s_waitcnt lgkmcnt(6)
	v_mfma_f32_32x32x16_bf16 v[18:33], v[178:181], v[170:173], v[18:33]
	ds_read_b128 v[206:209], v157 offset:59968
	global_load_dwordx4 v[122:125], v216, s[86:87] offset:384
	v_mfma_f32_32x32x16_bf16 v[2:17], v[178:181], v[174:177], v[2:17]
	ds_read_b128 v[210:213], v156 offset:23104
	global_load_dwordx4 v[126:129], v219, s[86:87] offset:384
	s_waitcnt lgkmcnt(6)
	v_mfma_f32_32x32x16_bf16 v[50:65], v[182:185], v[186:189], v[50:65]
	ds_read_b128 v[166:169], v156 offset:18528
	s_waitcnt vmcnt(8)
	ds_write_b128 v1, v[66:69]
	s_waitcnt lgkmcnt(7)
	v_mfma_f32_32x32x16_bf16 v[34:49], v[182:185], v[190:193], v[34:49]
	ds_read_b128 v[170:173], v157 offset:55392
	ds_write_b128 v1, v[90:93] offset:36864
	s_waitcnt lgkmcnt(8)
	v_mfma_f32_32x32x16_bf16 v[18:33], v[194:197], v[186:189], v[18:33]
	ds_read_b128 v[174:177], v157 offset:60000
	ds_write_b128 v1, v[70:73] offset:4608
	v_mfma_f32_32x32x16_bf16 v[2:17], v[194:197], v[190:193], v[2:17]
	ds_read_b128 v[178:181], v156 offset:23136
	ds_write_b128 v1, v[74:77] offset:41472
	s_waitcnt lgkmcnt(10)
	v_mfma_f32_32x32x16_bf16 v[50:65], v[198:201], v[202:205], v[50:65]
	ds_write_b128 v1, v[78:81] offset:9216
	s_waitcnt lgkmcnt(10)
	v_mfma_f32_32x32x16_bf16 v[34:49], v[198:201], v[206:209], v[34:49]
	ds_write_b128 v1, v[82:85] offset:46080
	s_waitcnt lgkmcnt(10)
	v_mfma_f32_32x32x16_bf16 v[18:33], v[210:213], v[202:205], v[18:33]
	ds_write_b128 v1, v[86:89] offset:13824
	v_mfma_f32_32x32x16_bf16 v[2:17], v[210:213], v[206:209], v[2:17]
	ds_write_b128 v1, v[102:105] offset:50688
	s_waitcnt lgkmcnt(9)
	v_mfma_f32_32x32x16_bf16 v[50:65], v[166:169], v[170:173], v[50:65]
	s_waitcnt lgkmcnt(7)
	v_mfma_f32_32x32x16_bf16 v[34:49], v[166:169], v[174:177], v[34:49]
	s_waitcnt lgkmcnt(5)
	v_mfma_f32_32x32x16_bf16 v[18:33], v[178:181], v[170:173], v[18:33]
	v_mfma_f32_32x32x16_bf16 v[2:17], v[178:181], v[174:177], v[2:17]
	s_setprio 0
	s_add_i32 s8, s8, 2
	s_add_u32 s84, s84, 0x100
	s_addc_u32 s85, s85, 0
	s_add_u32 s86, s86, 0x100
	s_addc_u32 s87, s87, 0
	s_waitcnt lgkmcnt(0)
	s_barrier
	s_cmp_lt_u32 s8, 14
	s_cbranch_scc1 .Lfast1_top
	s_branch .LBB0_102
